# combine phase: xor-1/2/4/8 butterfly steps as DPP adds (bit-identical sums) instead of 4 serialized ds_bpermute round trips per chunk
# baseline (speedup 1.0000x reference)
.LBB0_568:
	s_nop 0
	v_lshl_add_u64 v[16:17], s[4:5], 0, v[0:1]
	v_add_co_u32_e32 v14, vcc, 0x24800000, v16
	v_lshl_add_u64 v[12:13], s[8:9], 0, v[0:1]
	s_nop 0
	v_addc_co_u32_e32 v15, vcc, 0, v17, vcc
	v_add_co_u32_e32 v16, vcc, 0x2c800000, v16
	global_load_dwordx4 v[20:23], v[14:15], off
	s_nop 0
	v_addc_co_u32_e32 v17, vcc, 0, v17, vcc
	global_load_dwordx4 v[24:27], v[16:17], off
	global_load_dwordx4 v[36:39], v[14:15], off offset:1024
	global_load_dwordx4 v[40:43], v[16:17], off offset:1024
	global_load_dwordx4 v[44:47], v[14:15], off offset:2048
	global_load_dwordx4 v[48:51], v[16:17], off offset:2048
	global_load_dwordx4 v[52:55], v[14:15], off offset:3072
	global_load_dwordx4 v[56:59], v[16:17], off offset:3072
	v_add_co_u32_e64 v12, s[0:1], s12, v12
	s_add_i32 s10, s10, s22
	s_nop 0
	v_addc_co_u32_e64 v13, s[0:1], 0, v13, s[0:1]
	s_add_u32 s4, s4, s6
	s_addc_u32 s5, s5, s7
	s_add_u32 s8, s8, s6
	s_addc_u32 s9, s9, s7
	s_cmp_lt_i32 s10, 0x8000
	s_waitcnt vmcnt(7)
	v_lshlrev_b32_e32 v29, 16, v21
	v_lshlrev_b32_e32 v28, 16, v20
	v_and_b32_e32 v21, 0xffff0000, v21
	s_waitcnt vmcnt(6)
	v_lshlrev_b32_e32 v33, 16, v25
	v_lshlrev_b32_e32 v32, 16, v24
	v_and_b32_e32 v20, 0xffff0000, v20
	v_lshlrev_b32_e32 v31, 16, v23
	v_lshlrev_b32_e32 v30, 16, v22
	v_and_b32_e32 v23, 0xffff0000, v23
	v_and_b32_e32 v22, 0xffff0000, v22
	v_and_b32_e32 v25, 0xffff0000, v25
	v_and_b32_e32 v24, 0xffff0000, v24
	v_lshlrev_b32_e32 v35, 16, v27
	v_lshlrev_b32_e32 v34, 16, v26
	v_and_b32_e32 v27, 0xffff0000, v27
	v_and_b32_e32 v26, 0xffff0000, v26
	v_pk_fma_f32 v[28:29], v[2:3], v[32:33], v[28:29] neg_lo:[1,0,0] neg_hi:[1,0,0]
	v_pk_fma_f32 v[20:21], v[2:3], v[24:25], v[20:21] neg_lo:[1,0,0] neg_hi:[1,0,0]
	v_pk_fma_f32 v[24:25], v[2:3], v[34:35], v[30:31] neg_lo:[1,0,0] neg_hi:[1,0,0]
	v_pk_fma_f32 v[22:23], v[2:3], v[26:27], v[22:23] neg_lo:[1,0,0] neg_hi:[1,0,0]
	v_pk_mul_f32 v[26:27], v[28:29], v[28:29]
	v_pk_mul_f32 v[30:31], v[24:25], v[24:25]
	v_pk_fma_f32 v[26:27], v[20:21], v[20:21], v[26:27]
	v_pk_fma_f32 v[30:31], v[22:23], v[22:23], v[30:31]
	v_add_f32_e32 v26, v26, v27
	v_add_f32_e32 v26, v30, v26
	v_add_f32_e32 v26, v31, v26
	s_nop 1
	v_add_f32_dpp v26, v26, v26 quad_perm:[1,0,3,2] row_mask:0xf bank_mask:0xf
	s_nop 1
	v_add_f32_dpp v26, v26, v26 quad_perm:[2,3,0,1] row_mask:0xf bank_mask:0xf
	s_nop 1
	v_add_f32_dpp v26, v26, v26 row_half_mirror row_mask:0xf bank_mask:0xf
	s_nop 1
	v_add_f32_dpp v26, v26, v26 row_mirror row_mask:0xf bank_mask:0xf
	ds_bpermute_b32 v27, v176, v26
	s_waitcnt lgkmcnt(0)
	v_add_f32_e32 v26, v26, v27
	v_fmamk_f32 v26, v26, 0x3b800000, v18
	v_mul_f32_e32 v27, 0x4f800000, v26
	v_cmp_gt_f32_e32 vcc, s3, v26
	s_nop 1
	v_cndmask_b32_e32 v26, v26, v27, vcc
	v_sqrt_f32_e32 v27, v26
	s_nop 0
	v_add_u32_e32 v30, -1, v27
	v_add_u32_e32 v31, 1, v27
	v_fma_f32 v32, -v30, v27, v26
	v_fma_f32 v33, -v31, v27, v26
	v_cmp_ge_f32_e64 s[0:1], 0, v32
	s_nop 1
	v_cndmask_b32_e64 v27, v27, v30, s[0:1]
	v_cmp_lt_f32_e64 s[0:1], 0, v33
	s_nop 1
	v_cndmask_b32_e64 v27, v27, v31, s[0:1]
	v_mul_f32_e32 v30, 0x37800000, v27
	v_cndmask_b32_e32 v27, v27, v30, vcc
	v_cmp_class_f32_e32 vcc, v26, v19
	s_nop 1
	v_cndmask_b32_e32 v26, v27, v26, vcc
	v_div_scale_f32 v27, s[0:1], v26, v26, 1.0
	v_rcp_f32_e32 v31, v27
	v_div_scale_f32 v30, vcc, 1.0, v26, 1.0
	v_fma_f32 v32, -v27, v31, 1.0
	v_fmac_f32_e32 v31, v32, v31
	v_mul_f32_e32 v32, v30, v31
	v_fma_f32 v33, -v27, v32, v30
	v_fmac_f32_e32 v32, v33, v31
	v_fma_f32 v27, -v27, v32, v30
	v_div_fmas_f32 v27, v27, v31, v32
	v_div_fixup_f32 v26, v27, v26, 1.0
	v_pk_mul_f32 v[28:29], v[28:29], v[26:27] op_sel_hi:[1,0]
	v_pk_mul_f32 v[24:25], v[24:25], v[26:27] op_sel_hi:[1,0]
	v_pk_mul_f32 v[20:21], v[20:21], v[26:27] op_sel_hi:[1,0]
	v_pk_mul_f32 v[22:23], v[22:23], v[26:27] op_sel_hi:[1,0]
	v_pk_mul_f32 v[26:27], v[4:5], v[28:29]
	v_pk_mul_f32 v[24:25], v[8:9], v[24:25]
	v_pk_mul_f32 v[20:21], v[6:7], v[20:21]
	v_pk_mul_f32 v[22:23], v[10:11], v[22:23]
	v_bfe_u32 v32, v26, 16, 1
	v_bfe_u32 v33, v27, 16, 1
	v_bfe_u32 v34, v24, 16, 1
	v_bfe_u32 v35, v25, 16, 1
	v_bfe_u32 v28, v23, 16, 1
	v_bfe_u32 v29, v22, 16, 1
	v_bfe_u32 v30, v21, 16, 1
	v_bfe_u32 v31, v20, 16, 1
	v_add3_u32 v25, v25, v35, s11
	v_add3_u32 v24, v24, v34, s11
	v_add3_u32 v27, v27, v33, s11
	v_add3_u32 v26, v26, v32, s11
	v_add3_u32 v20, v20, v31, s11
	v_add3_u32 v21, v21, v30, s11
	v_add3_u32 v22, v22, v29, s11
	v_add3_u32 v23, v23, v28, s11
	v_lshrrev_b32_e32 v26, 16, v26
	v_lshrrev_b32_e32 v27, 16, v27
	v_lshrrev_b32_e32 v24, 16, v24
	v_lshrrev_b32_e32 v25, 16, v25
	v_and_or_b32 v23, v23, s2, v25
	v_and_or_b32 v22, v22, s2, v24
	v_and_or_b32 v21, v21, s2, v27
	v_and_or_b32 v20, v20, s2, v26
	global_store_dwordx4 v[12:13], v[20:23], off
	s_waitcnt vmcnt(5)
	s_nop 1
	v_mov_b32_e32 v20, v36
	v_mov_b32_e32 v21, v37
	v_mov_b32_e32 v22, v38
	v_mov_b32_e32 v23, v39
	v_mov_b32_e32 v24, v40
	v_mov_b32_e32 v25, v41
	v_mov_b32_e32 v26, v42
	v_mov_b32_e32 v27, v43
	v_lshlrev_b32_e32 v29, 16, v21
	v_lshlrev_b32_e32 v28, 16, v20
	v_lshlrev_b32_e32 v31, 16, v25
	v_lshlrev_b32_e32 v30, 16, v24
	v_and_b32_e32 v21, 0xffff0000, v21
	v_and_b32_e32 v20, 0xffff0000, v20
	v_and_b32_e32 v25, 0xffff0000, v25
	v_and_b32_e32 v24, 0xffff0000, v24
	v_lshlrev_b32_e32 v33, 16, v23
	v_lshlrev_b32_e32 v32, 16, v22
	v_lshlrev_b32_e32 v35, 16, v27
	v_lshlrev_b32_e32 v34, 16, v26
	v_and_b32_e32 v23, 0xffff0000, v23
	v_and_b32_e32 v22, 0xffff0000, v22
	v_and_b32_e32 v27, 0xffff0000, v27
	v_and_b32_e32 v26, 0xffff0000, v26
	v_pk_fma_f32 v[28:29], v[2:3], v[30:31], v[28:29] neg_lo:[1,0,0] neg_hi:[1,0,0]
	v_pk_fma_f32 v[20:21], v[2:3], v[24:25], v[20:21] neg_lo:[1,0,0] neg_hi:[1,0,0]
	v_pk_fma_f32 v[24:25], v[2:3], v[34:35], v[32:33] neg_lo:[1,0,0] neg_hi:[1,0,0]
	v_pk_fma_f32 v[22:23], v[2:3], v[26:27], v[22:23] neg_lo:[1,0,0] neg_hi:[1,0,0]
	v_pk_mul_f32 v[26:27], v[28:29], v[28:29]
	v_pk_mul_f32 v[30:31], v[24:25], v[24:25]
	v_pk_fma_f32 v[26:27], v[20:21], v[20:21], v[26:27]
	v_pk_fma_f32 v[30:31], v[22:23], v[22:23], v[30:31]
	v_add_f32_e32 v26, v26, v27
	v_add_f32_e32 v26, v30, v26
	v_add_f32_e32 v26, v31, v26
	s_nop 1
	v_add_f32_dpp v26, v26, v26 quad_perm:[1,0,3,2] row_mask:0xf bank_mask:0xf
	s_nop 1
	v_add_f32_dpp v26, v26, v26 quad_perm:[2,3,0,1] row_mask:0xf bank_mask:0xf
	s_nop 1
	v_add_f32_dpp v26, v26, v26 row_half_mirror row_mask:0xf bank_mask:0xf
	s_nop 1
	v_add_f32_dpp v26, v26, v26 row_mirror row_mask:0xf bank_mask:0xf
	ds_bpermute_b32 v27, v176, v26
	s_waitcnt lgkmcnt(0)
	v_add_f32_e32 v26, v26, v27
	v_fmamk_f32 v26, v26, 0x3b800000, v18
	v_mul_f32_e32 v27, 0x4f800000, v26
	v_cmp_gt_f32_e32 vcc, s3, v26
	s_nop 1
	v_cndmask_b32_e32 v26, v26, v27, vcc
	v_sqrt_f32_e32 v27, v26
	s_nop 0
	v_add_u32_e32 v30, -1, v27
	v_add_u32_e32 v31, 1, v27
	v_fma_f32 v32, -v30, v27, v26
	v_fma_f32 v33, -v31, v27, v26
	v_cmp_ge_f32_e64 s[0:1], 0, v32
	s_nop 1
	v_cndmask_b32_e64 v27, v27, v30, s[0:1]
	v_cmp_lt_f32_e64 s[0:1], 0, v33
	s_nop 1
	v_cndmask_b32_e64 v27, v27, v31, s[0:1]
	v_mul_f32_e32 v30, 0x37800000, v27
	v_cndmask_b32_e32 v27, v27, v30, vcc
	v_cmp_class_f32_e32 vcc, v26, v19
	s_nop 1
	v_cndmask_b32_e32 v26, v27, v26, vcc
	v_div_scale_f32 v27, s[0:1], v26, v26, 1.0
	v_rcp_f32_e32 v31, v27
	v_div_scale_f32 v30, vcc, 1.0, v26, 1.0
	v_fma_f32 v32, -v27, v31, 1.0
	v_fmac_f32_e32 v31, v32, v31
	v_mul_f32_e32 v32, v30, v31
	v_fma_f32 v33, -v27, v32, v30
	v_fmac_f32_e32 v32, v33, v31
	v_fma_f32 v27, -v27, v32, v30
	v_div_fmas_f32 v27, v27, v31, v32
	v_div_fixup_f32 v26, v27, v26, 1.0
	v_pk_mul_f32 v[28:29], v[28:29], v[26:27] op_sel_hi:[1,0]
	v_pk_mul_f32 v[24:25], v[24:25], v[26:27] op_sel_hi:[1,0]
	v_pk_mul_f32 v[20:21], v[20:21], v[26:27] op_sel_hi:[1,0]
	v_pk_mul_f32 v[22:23], v[22:23], v[26:27] op_sel_hi:[1,0]
	v_pk_mul_f32 v[26:27], v[4:5], v[28:29]
	v_pk_mul_f32 v[24:25], v[8:9], v[24:25]
	v_pk_mul_f32 v[20:21], v[6:7], v[20:21]
	v_pk_mul_f32 v[22:23], v[10:11], v[22:23]
	v_bfe_u32 v32, v26, 16, 1
	v_bfe_u32 v33, v27, 16, 1
	v_bfe_u32 v34, v24, 16, 1
	v_bfe_u32 v35, v25, 16, 1
	v_bfe_u32 v28, v23, 16, 1
	v_bfe_u32 v29, v22, 16, 1
	v_bfe_u32 v30, v21, 16, 1
	v_bfe_u32 v31, v20, 16, 1
	v_add3_u32 v25, v25, v35, s11
	v_add3_u32 v24, v24, v34, s11
	v_add3_u32 v27, v27, v33, s11
	v_add3_u32 v26, v26, v32, s11
	v_add3_u32 v20, v20, v31, s11
	v_add3_u32 v21, v21, v30, s11
	v_add3_u32 v22, v22, v29, s11
	v_add3_u32 v23, v23, v28, s11
	v_lshrrev_b32_e32 v26, 16, v26
	v_lshrrev_b32_e32 v27, 16, v27
	v_lshrrev_b32_e32 v24, 16, v24
	v_lshrrev_b32_e32 v25, 16, v25
	v_and_or_b32 v23, v23, s2, v25
	v_and_or_b32 v22, v22, s2, v24
	v_and_or_b32 v21, v21, s2, v27
	v_and_or_b32 v20, v20, s2, v26
	global_store_dwordx4 v[12:13], v[20:23], off offset:1024
	s_waitcnt vmcnt(4)
	s_nop 1
	v_mov_b32_e32 v20, v44
	v_mov_b32_e32 v21, v45
	v_mov_b32_e32 v22, v46
	v_mov_b32_e32 v23, v47
	v_mov_b32_e32 v24, v48
	v_mov_b32_e32 v25, v49
	v_mov_b32_e32 v26, v50
	v_mov_b32_e32 v27, v51
	v_lshlrev_b32_e32 v29, 16, v21
	v_lshlrev_b32_e32 v28, 16, v20
	v_lshlrev_b32_e32 v31, 16, v25
	v_lshlrev_b32_e32 v30, 16, v24
	v_and_b32_e32 v21, 0xffff0000, v21
	v_and_b32_e32 v20, 0xffff0000, v20
	v_and_b32_e32 v25, 0xffff0000, v25
	v_and_b32_e32 v24, 0xffff0000, v24
	v_lshlrev_b32_e32 v33, 16, v23
	v_lshlrev_b32_e32 v32, 16, v22
	v_lshlrev_b32_e32 v35, 16, v27
	v_lshlrev_b32_e32 v34, 16, v26
	v_and_b32_e32 v23, 0xffff0000, v23
	v_and_b32_e32 v22, 0xffff0000, v22
	v_and_b32_e32 v27, 0xffff0000, v27
	v_and_b32_e32 v26, 0xffff0000, v26
	v_pk_fma_f32 v[28:29], v[2:3], v[30:31], v[28:29] neg_lo:[1,0,0] neg_hi:[1,0,0]
	v_pk_fma_f32 v[20:21], v[2:3], v[24:25], v[20:21] neg_lo:[1,0,0] neg_hi:[1,0,0]
	v_pk_fma_f32 v[24:25], v[2:3], v[34:35], v[32:33] neg_lo:[1,0,0] neg_hi:[1,0,0]
	v_pk_fma_f32 v[22:23], v[2:3], v[26:27], v[22:23] neg_lo:[1,0,0] neg_hi:[1,0,0]
	v_pk_mul_f32 v[26:27], v[28:29], v[28:29]
	v_pk_mul_f32 v[30:31], v[24:25], v[24:25]
	v_pk_fma_f32 v[26:27], v[20:21], v[20:21], v[26:27]
	v_pk_fma_f32 v[30:31], v[22:23], v[22:23], v[30:31]
	v_add_f32_e32 v26, v26, v27
	v_add_f32_e32 v26, v30, v26
	v_add_f32_e32 v26, v31, v26
	s_nop 1
	v_add_f32_dpp v26, v26, v26 quad_perm:[1,0,3,2] row_mask:0xf bank_mask:0xf
	s_nop 1
	v_add_f32_dpp v26, v26, v26 quad_perm:[2,3,0,1] row_mask:0xf bank_mask:0xf
	s_nop 1
	v_add_f32_dpp v26, v26, v26 row_half_mirror row_mask:0xf bank_mask:0xf
	s_nop 1
	v_add_f32_dpp v26, v26, v26 row_mirror row_mask:0xf bank_mask:0xf
	ds_bpermute_b32 v27, v176, v26
	s_waitcnt lgkmcnt(0)
	v_add_f32_e32 v26, v26, v27
	v_fmamk_f32 v26, v26, 0x3b800000, v18
	v_mul_f32_e32 v27, 0x4f800000, v26
	v_cmp_gt_f32_e32 vcc, s3, v26
	s_nop 1
	v_cndmask_b32_e32 v26, v26, v27, vcc
	v_sqrt_f32_e32 v27, v26
	s_nop 0
	v_add_u32_e32 v30, -1, v27
	v_add_u32_e32 v31, 1, v27
	v_fma_f32 v32, -v30, v27, v26
	v_fma_f32 v33, -v31, v27, v26
	v_cmp_ge_f32_e64 s[0:1], 0, v32
	s_nop 1
	v_cndmask_b32_e64 v27, v27, v30, s[0:1]
	v_cmp_lt_f32_e64 s[0:1], 0, v33
	s_nop 1
	v_cndmask_b32_e64 v27, v27, v31, s[0:1]
	v_mul_f32_e32 v30, 0x37800000, v27
	v_cndmask_b32_e32 v27, v27, v30, vcc
	v_cmp_class_f32_e32 vcc, v26, v19
	s_nop 1
	v_cndmask_b32_e32 v26, v27, v26, vcc
	v_div_scale_f32 v27, s[0:1], v26, v26, 1.0
	v_rcp_f32_e32 v31, v27
	v_div_scale_f32 v30, vcc, 1.0, v26, 1.0
	v_fma_f32 v32, -v27, v31, 1.0
	v_fmac_f32_e32 v31, v32, v31
	v_mul_f32_e32 v32, v30, v31
	v_fma_f32 v33, -v27, v32, v30
	v_fmac_f32_e32 v32, v33, v31
	v_fma_f32 v27, -v27, v32, v30
	v_div_fmas_f32 v27, v27, v31, v32
	v_div_fixup_f32 v26, v27, v26, 1.0
	v_pk_mul_f32 v[28:29], v[28:29], v[26:27] op_sel_hi:[1,0]
	v_pk_mul_f32 v[24:25], v[24:25], v[26:27] op_sel_hi:[1,0]
	v_pk_mul_f32 v[20:21], v[20:21], v[26:27] op_sel_hi:[1,0]
	v_pk_mul_f32 v[22:23], v[22:23], v[26:27] op_sel_hi:[1,0]
	v_pk_mul_f32 v[26:27], v[4:5], v[28:29]
	v_pk_mul_f32 v[24:25], v[8:9], v[24:25]
	v_pk_mul_f32 v[20:21], v[6:7], v[20:21]
	v_pk_mul_f32 v[22:23], v[10:11], v[22:23]
	v_bfe_u32 v32, v26, 16, 1
	v_bfe_u32 v33, v27, 16, 1
	v_bfe_u32 v34, v24, 16, 1
	v_bfe_u32 v35, v25, 16, 1
	v_bfe_u32 v28, v23, 16, 1
	v_bfe_u32 v29, v22, 16, 1
	v_bfe_u32 v30, v21, 16, 1
	v_bfe_u32 v31, v20, 16, 1
	v_add3_u32 v25, v25, v35, s11
	v_add3_u32 v24, v24, v34, s11
	v_add3_u32 v27, v27, v33, s11
	v_add3_u32 v26, v26, v32, s11
	v_add3_u32 v20, v20, v31, s11
	v_add3_u32 v21, v21, v30, s11
	v_add3_u32 v22, v22, v29, s11
	v_add3_u32 v23, v23, v28, s11
	v_lshrrev_b32_e32 v26, 16, v26
	v_lshrrev_b32_e32 v27, 16, v27
	v_lshrrev_b32_e32 v24, 16, v24
	v_lshrrev_b32_e32 v25, 16, v25
	v_and_or_b32 v23, v23, s2, v25
	v_and_or_b32 v22, v22, s2, v24
	v_and_or_b32 v21, v21, s2, v27
	v_and_or_b32 v20, v20, s2, v26
	global_store_dwordx4 v[12:13], v[20:23], off offset:2048
	s_waitcnt vmcnt(3)
	s_nop 1
	v_mov_b32_e32 v20, v52
	v_mov_b32_e32 v21, v53
	v_mov_b32_e32 v22, v54
	v_mov_b32_e32 v23, v55
	v_mov_b32_e32 v14, v56
	v_mov_b32_e32 v15, v57
	v_mov_b32_e32 v16, v58
	v_mov_b32_e32 v17, v59
	v_lshlrev_b32_e32 v25, 16, v21
	v_lshlrev_b32_e32 v24, 16, v20
	v_lshlrev_b32_e32 v27, 16, v15
	v_lshlrev_b32_e32 v26, 16, v14
	v_and_b32_e32 v21, 0xffff0000, v21
	v_and_b32_e32 v20, 0xffff0000, v20
	v_and_b32_e32 v15, 0xffff0000, v15
	v_and_b32_e32 v14, 0xffff0000, v14
	v_lshlrev_b32_e32 v29, 16, v23
	v_lshlrev_b32_e32 v28, 16, v22
	v_lshlrev_b32_e32 v31, 16, v17
	v_lshlrev_b32_e32 v30, 16, v16
	v_and_b32_e32 v23, 0xffff0000, v23
	v_and_b32_e32 v22, 0xffff0000, v22
	v_and_b32_e32 v17, 0xffff0000, v17
	v_and_b32_e32 v16, 0xffff0000, v16
	v_pk_fma_f32 v[24:25], v[2:3], v[26:27], v[24:25] neg_lo:[1,0,0] neg_hi:[1,0,0]
	v_pk_fma_f32 v[14:15], v[2:3], v[14:15], v[20:21] neg_lo:[1,0,0] neg_hi:[1,0,0]
	v_pk_fma_f32 v[20:21], v[2:3], v[30:31], v[28:29] neg_lo:[1,0,0] neg_hi:[1,0,0]
	v_pk_fma_f32 v[16:17], v[2:3], v[16:17], v[22:23] neg_lo:[1,0,0] neg_hi:[1,0,0]
	v_pk_mul_f32 v[22:23], v[24:25], v[24:25]
	v_pk_mul_f32 v[26:27], v[20:21], v[20:21]
	v_pk_fma_f32 v[22:23], v[14:15], v[14:15], v[22:23]
	v_pk_fma_f32 v[26:27], v[16:17], v[16:17], v[26:27]
	v_add_f32_e32 v22, v22, v23
	v_add_f32_e32 v22, v26, v22
	v_add_f32_e32 v22, v27, v22
	s_nop 1
	v_add_f32_dpp v22, v22, v22 quad_perm:[1,0,3,2] row_mask:0xf bank_mask:0xf
	s_nop 1
	v_add_f32_dpp v22, v22, v22 quad_perm:[2,3,0,1] row_mask:0xf bank_mask:0xf
	s_nop 1
	v_add_f32_dpp v22, v22, v22 row_half_mirror row_mask:0xf bank_mask:0xf
	s_nop 1
	v_add_f32_dpp v22, v22, v22 row_mirror row_mask:0xf bank_mask:0xf
	ds_bpermute_b32 v23, v176, v22
	s_waitcnt lgkmcnt(0)
	v_add_f32_e32 v22, v22, v23
	v_fmamk_f32 v22, v22, 0x3b800000, v18
	v_mul_f32_e32 v23, 0x4f800000, v22
	v_cmp_gt_f32_e32 vcc, s3, v22
	s_nop 1
	v_cndmask_b32_e32 v22, v22, v23, vcc
	v_sqrt_f32_e32 v23, v22
	s_nop 0
	v_add_u32_e32 v26, -1, v23
	v_add_u32_e32 v27, 1, v23
	v_fma_f32 v28, -v26, v23, v22
	v_fma_f32 v29, -v27, v23, v22
	v_cmp_ge_f32_e64 s[0:1], 0, v28
	s_nop 1
	v_cndmask_b32_e64 v23, v23, v26, s[0:1]
	v_cmp_lt_f32_e64 s[0:1], 0, v29
	s_nop 1
	v_cndmask_b32_e64 v23, v23, v27, s[0:1]
	v_mul_f32_e32 v26, 0x37800000, v23
	v_cndmask_b32_e32 v23, v23, v26, vcc
	v_cmp_class_f32_e32 vcc, v22, v19
	s_nop 1
	v_cndmask_b32_e32 v22, v23, v22, vcc
	v_div_scale_f32 v23, s[0:1], v22, v22, 1.0
	v_rcp_f32_e32 v27, v23
	v_div_scale_f32 v26, vcc, 1.0, v22, 1.0
	v_fma_f32 v28, -v23, v27, 1.0
	v_fmac_f32_e32 v27, v28, v27
	v_mul_f32_e32 v28, v26, v27
	v_fma_f32 v29, -v23, v28, v26
	v_fmac_f32_e32 v28, v29, v27
	v_fma_f32 v23, -v23, v28, v26
	v_div_fmas_f32 v23, v23, v27, v28
	v_div_fixup_f32 v22, v23, v22, 1.0
	v_pk_mul_f32 v[24:25], v[24:25], v[22:23] op_sel_hi:[1,0]
	v_pk_mul_f32 v[20:21], v[20:21], v[22:23] op_sel_hi:[1,0]
	v_pk_mul_f32 v[14:15], v[14:15], v[22:23] op_sel_hi:[1,0]
	v_pk_mul_f32 v[16:17], v[16:17], v[22:23] op_sel_hi:[1,0]
	v_pk_mul_f32 v[22:23], v[4:5], v[24:25]
	v_pk_mul_f32 v[20:21], v[8:9], v[20:21]
	v_pk_mul_f32 v[14:15], v[6:7], v[14:15]
	v_pk_mul_f32 v[16:17], v[10:11], v[16:17]
	v_bfe_u32 v28, v22, 16, 1
	v_bfe_u32 v29, v23, 16, 1
	v_bfe_u32 v30, v20, 16, 1
	v_bfe_u32 v31, v21, 16, 1
	v_bfe_u32 v24, v17, 16, 1
	v_bfe_u32 v25, v16, 16, 1
	v_bfe_u32 v26, v15, 16, 1
	v_bfe_u32 v27, v14, 16, 1
	v_add3_u32 v21, v21, v31, s11
	v_add3_u32 v20, v20, v30, s11
	v_add3_u32 v23, v23, v29, s11
	v_add3_u32 v22, v22, v28, s11
	v_add3_u32 v14, v14, v27, s11
	v_add3_u32 v15, v15, v26, s11
	v_add3_u32 v16, v16, v25, s11
	v_add3_u32 v17, v17, v24, s11
	v_lshrrev_b32_e32 v22, 16, v22
	v_lshrrev_b32_e32 v23, 16, v23
	v_lshrrev_b32_e32 v20, 16, v20
	v_lshrrev_b32_e32 v21, 16, v21
	v_and_or_b32 v17, v17, s2, v21
	v_and_or_b32 v16, v16, s2, v20
	v_and_or_b32 v15, v15, s2, v23
	v_and_or_b32 v14, v14, s2, v22
	global_store_dwordx4 v[12:13], v[14:17], off offset:3072
	s_cbranch_scc1 .LBB0_568
